# attention PV: value fragments read singly into a 4/6-quad ring 3-5 fragments ahead of their MFMAs behind counted lgkmcnt waits
# baseline (speedup 1.0000x reference)
.LBB0_719:
	v_add_u32_e32 v1, s61, v226
	s_mov_b32 s0, 0x8800
	v_add3_u32 v188, v1, v225, s0
	v_exp_f32_e32 v1, v176
	v_exp_f32_e32 v2, v177
	v_exp_f32_e32 v3, v178
	v_exp_f32_e32 v177, v179
	v_cvt_pk_bf16_f32 v176, v1, v2
	v_cvt_pk_bf16_f32 v177, v3, v177
	v_mov_b32_e32 v1, v0
	v_mov_b32_e32 v2, v0
	v_mov_b32_e32 v3, v0
	v_exp_f32_e32 v178, v180
	v_exp_f32_e32 v179, v181
	v_exp_f32_e32 v180, v182
	v_exp_f32_e32 v181, v183
	v_cvt_pk_bf16_f32 v178, v178, v179
	v_cvt_pk_bf16_f32 v179, v180, v181
	v_mov_b32_e32 v173, v172
	v_mfma_f32_16x16x32_bf16 v[164:167], v[0:3], v[176:179], v[164:167]
	v_mov_b32_e32 v174, v172
	v_mov_b32_e32 v175, v172
	ds_read_b128 v[180:183], v188 offset:0
	ds_read_b128 v[230:233], v188 offset:2304
	ds_read_b128 v[234:237], v188 offset:4608
	ds_read_b128 v[238:241], v188 offset:6912
	s_waitcnt lgkmcnt(3)
	v_mfma_f32_16x16x32_bf16 v[160:163], v[180:183], v[184:187], v[160:163]
	v_mfma_f32_16x16x32_bf16 v[156:159], v[180:183], v[176:179], v[156:159]
	ds_read_b128 v[180:183], v188 offset:9216
	s_waitcnt lgkmcnt(3)
	v_mfma_f32_16x16x32_bf16 v[152:155], v[230:233], v[184:187], v[152:155]
	v_mfma_f32_16x16x32_bf16 v[148:151], v[230:233], v[176:179], v[148:151]
	ds_read_b128 v[230:233], v188 offset:11520
	s_waitcnt lgkmcnt(3)
	v_mfma_f32_16x16x32_bf16 v[144:147], v[234:237], v[184:187], v[144:147]
	v_mfma_f32_16x16x32_bf16 v[140:143], v[234:237], v[176:179], v[140:143]
	ds_read_b128 v[234:237], v188 offset:13824
	s_waitcnt lgkmcnt(3)
	v_mfma_f32_16x16x32_bf16 v[136:139], v[238:241], v[184:187], v[136:139]
	v_mfma_f32_16x16x32_bf16 v[132:135], v[238:241], v[176:179], v[132:135]
	ds_read_b128 v[238:241], v188 offset:16128
	s_waitcnt lgkmcnt(3)
	v_mfma_f32_16x16x32_bf16 v[96:99], v[180:183], v[184:187], v[96:99]
	v_mfma_f32_16x16x32_bf16 v[92:95], v[180:183], v[176:179], v[92:95]
	ds_read_b128 v[180:183], v188 offset:18432
	s_waitcnt lgkmcnt(3)
	v_mfma_f32_16x16x32_bf16 v[88:91], v[230:233], v[184:187], v[88:91]
	v_mfma_f32_16x16x32_bf16 v[84:87], v[230:233], v[176:179], v[84:87]
	ds_read_b128 v[230:233], v188 offset:20736
	s_waitcnt lgkmcnt(3)
	v_mfma_f32_16x16x32_bf16 v[80:83], v[234:237], v[184:187], v[80:83]
	v_mfma_f32_16x16x32_bf16 v[76:79], v[234:237], v[176:179], v[76:79]
	ds_read_b128 v[234:237], v188 offset:23040
	s_waitcnt lgkmcnt(3)
	v_mfma_f32_16x16x32_bf16 v[72:75], v[238:241], v[184:187], v[72:75]
	v_mfma_f32_16x16x32_bf16 v[68:71], v[238:241], v[176:179], v[68:71]
	ds_read_b128 v[238:241], v188 offset:25344
	s_waitcnt lgkmcnt(3)
	v_mfma_f32_16x16x32_bf16 v[64:67], v[180:183], v[184:187], v[64:67]
	v_mfma_f32_16x16x32_bf16 v[60:63], v[180:183], v[176:179], v[60:63]
	ds_read_b128 v[180:183], v188 offset:27648
	s_waitcnt lgkmcnt(3)
	v_mfma_f32_16x16x32_bf16 v[56:59], v[230:233], v[184:187], v[56:59]
	v_mfma_f32_16x16x32_bf16 v[52:55], v[230:233], v[176:179], v[52:55]
	ds_read_b128 v[230:233], v188 offset:29952
	s_waitcnt lgkmcnt(3)
	v_mfma_f32_16x16x32_bf16 v[48:51], v[234:237], v[184:187], v[48:51]
	v_mfma_f32_16x16x32_bf16 v[44:47], v[234:237], v[176:179], v[44:47]
	ds_read_b128 v[234:237], v188 offset:32256
	s_waitcnt lgkmcnt(3)
	v_mfma_f32_16x16x32_bf16 v[40:43], v[238:241], v[184:187], v[40:43]
	v_mfma_f32_16x16x32_bf16 v[36:39], v[238:241], v[176:179], v[36:39]
	ds_read_b128 v[238:241], v188 offset:34560
	s_waitcnt lgkmcnt(3)
	v_mfma_f32_16x16x32_bf16 v[32:35], v[180:183], v[184:187], v[32:35]
	v_mfma_f32_16x16x32_bf16 v[28:31], v[180:183], v[176:179], v[28:31]
	s_waitcnt lgkmcnt(2)
	v_mfma_f32_16x16x32_bf16 v[24:27], v[230:233], v[184:187], v[24:27]
	v_mfma_f32_16x16x32_bf16 v[20:23], v[230:233], v[176:179], v[20:23]
	s_waitcnt lgkmcnt(1)
	v_mfma_f32_16x16x32_bf16 v[16:19], v[234:237], v[184:187], v[16:19]
	v_mfma_f32_16x16x32_bf16 v[12:15], v[234:237], v[176:179], v[12:15]
	s_waitcnt lgkmcnt(0)
	v_mfma_f32_16x16x32_bf16 v[8:11], v[238:241], v[184:187], v[8:11]
	v_mfma_f32_16x16x32_bf16 v[4:7], v[238:241], v[176:179], v[4:7]
	ds_read_b128 v[176:179], v229 offset:8704
	ds_read_b128 v[230:233], v229 offset:8768
	ds_read_b128 v[234:237], v229 offset:8832
	ds_read_b128 v[238:241], v229 offset:8896
	v_xor_b32_e32 v184, 0x80000000, v228
	v_mov_b32_e32 v185, v184
	v_mov_b32_e32 v186, v184
	v_mov_b32_e32 v187, v184
	s_waitcnt lgkmcnt(3)
	s_nop 0
	v_mfma_f32_16x16x32_bf16 v[180:183], v[176:179], v[100:103], v[184:187]
	v_mfma_f32_16x16x32_bf16 v[176:179], v[176:179], v[116:119], v[172:175]
	s_waitcnt lgkmcnt(2)
	v_mfma_f32_16x16x32_bf16 v[180:183], v[230:233], v[104:107], v[180:183]
	v_mfma_f32_16x16x32_bf16 v[176:179], v[230:233], v[120:123], v[176:179]
	ds_read_b128 v[230:233], v229 offset:13056
	s_waitcnt lgkmcnt(2)
	v_mfma_f32_16x16x32_bf16 v[180:183], v[234:237], v[108:111], v[180:183]
	v_mfma_f32_16x16x32_bf16 v[176:179], v[234:237], v[124:127], v[176:179]
	ds_read_b128 v[234:237], v229 offset:13120
	s_waitcnt lgkmcnt(2)
	v_mfma_f32_16x16x32_bf16 v[180:183], v[238:241], v[112:115], v[180:183]
	v_mfma_f32_16x16x32_bf16 v[176:179], v[238:241], v[128:131], v[176:179]
	ds_read_b128 v[238:241], v229 offset:13184
	s_waitcnt lgkmcnt(2)
	v_mfma_f32_16x16x32_bf16 v[184:187], v[230:233], v[100:103], v[184:187]
	v_mfma_f32_16x16x32_bf16 v[172:175], v[230:233], v[116:119], v[172:175]
	ds_read_b128 v[230:233], v229 offset:13248
	s_waitcnt lgkmcnt(2)
	v_mfma_f32_16x16x32_bf16 v[184:187], v[234:237], v[104:107], v[184:187]
	v_mfma_f32_16x16x32_bf16 v[172:175], v[234:237], v[120:123], v[172:175]
	s_waitcnt lgkmcnt(1)
	v_mfma_f32_16x16x32_bf16 v[184:187], v[238:241], v[108:111], v[184:187]
	v_mfma_f32_16x16x32_bf16 v[172:175], v[238:241], v[124:127], v[172:175]
	s_waitcnt lgkmcnt(0)
	v_mfma_f32_16x16x32_bf16 v[184:187], v[230:233], v[112:115], v[184:187]
	v_mfma_f32_16x16x32_bf16 v[172:175], v[230:233], v[128:131], v[172:175]
	v_max_f32_e32 v189, v181, v181
	v_max_f32_e32 v190, v180, v180
	v_max_f32_e32 v189, v190, v189
	v_max_f32_e32 v190, v183, v183
	v_max_f32_e32 v191, v182, v182
	v_max_f32_e32 v190, v191, v190
	s_nop 0
	v_max_f32_e32 v191, v187, v187
	v_max_f32_e32 v212, v186, v186
	v_max_f32_e32 v191, v212, v191
	v_max3_f32 v191, v184, v185, v191
	v_max3_f32 v189, v189, v190, v191
	v_cmp_lt_f32_e32 vcc, s77, v189
	s_cbranch_vccz .LBB0_721
	v_mov_b32_e32 v190, v189
	s_nop 1
	v_permlane16_swap_b32_e32 v189, v190
	v_max_f32_e32 v190, v190, v190
	v_max_f32_e32 v189, v189, v189
	v_max_f32_e32 v189, v189, v190
	v_mov_b32_e32 v190, v189
	s_nop 1
	v_permlane32_swap_b32_e32 v189, v190
	v_max3_f32 v189, v189, v190, 0
	v_exp_f32_e64 v190, -v189
	v_add_f32_e32 v228, v228, v189
	v_sub_f32_e32 v180, v180, v189
	v_sub_f32_e32 v181, v181, v189
	v_pk_mul_f32 v[170:171], v[170:171], v[190:191] op_sel_hi:[1,0]
	v_pk_mul_f32 v[168:169], v[168:169], v[190:191] op_sel_hi:[1,0]
	v_pk_mul_f32 v[162:163], v[162:163], v[190:191] op_sel_hi:[1,0]
	v_pk_mul_f32 v[160:161], v[160:161], v[190:191] op_sel_hi:[1,0]
	v_pk_mul_f32 v[154:155], v[154:155], v[190:191] op_sel_hi:[1,0]
	v_pk_mul_f32 v[152:153], v[152:153], v[190:191] op_sel_hi:[1,0]
	v_pk_mul_f32 v[146:147], v[146:147], v[190:191] op_sel_hi:[1,0]
	v_pk_mul_f32 v[144:145], v[144:145], v[190:191] op_sel_hi:[1,0]
	v_pk_mul_f32 v[138:139], v[138:139], v[190:191] op_sel_hi:[1,0]
	v_pk_mul_f32 v[136:137], v[136:137], v[190:191] op_sel_hi:[1,0]
	v_pk_mul_f32 v[98:99], v[98:99], v[190:191] op_sel_hi:[1,0]
	v_pk_mul_f32 v[96:97], v[96:97], v[190:191] op_sel_hi:[1,0]
	v_pk_mul_f32 v[90:91], v[90:91], v[190:191] op_sel_hi:[1,0]
	v_pk_mul_f32 v[88:89], v[88:89], v[190:191] op_sel_hi:[1,0]
	v_pk_mul_f32 v[82:83], v[82:83], v[190:191] op_sel_hi:[1,0]
	v_pk_mul_f32 v[80:81], v[80:81], v[190:191] op_sel_hi:[1,0]
	v_pk_mul_f32 v[74:75], v[74:75], v[190:191] op_sel_hi:[1,0]
	v_pk_mul_f32 v[72:73], v[72:73], v[190:191] op_sel_hi:[1,0]
	v_pk_mul_f32 v[66:67], v[66:67], v[190:191] op_sel_hi:[1,0]
	v_pk_mul_f32 v[64:65], v[64:65], v[190:191] op_sel_hi:[1,0]
	v_pk_mul_f32 v[58:59], v[58:59], v[190:191] op_sel_hi:[1,0]
	v_pk_mul_f32 v[56:57], v[56:57], v[190:191] op_sel_hi:[1,0]
	v_pk_mul_f32 v[50:51], v[50:51], v[190:191] op_sel_hi:[1,0]
	v_pk_mul_f32 v[48:49], v[48:49], v[190:191] op_sel_hi:[1,0]
	v_pk_mul_f32 v[42:43], v[42:43], v[190:191] op_sel_hi:[1,0]
	v_pk_mul_f32 v[40:41], v[40:41], v[190:191] op_sel_hi:[1,0]
	v_pk_mul_f32 v[34:35], v[34:35], v[190:191] op_sel_hi:[1,0]
	v_pk_mul_f32 v[32:33], v[32:33], v[190:191] op_sel_hi:[1,0]
	v_pk_mul_f32 v[26:27], v[26:27], v[190:191] op_sel_hi:[1,0]
	v_pk_mul_f32 v[24:25], v[24:25], v[190:191] op_sel_hi:[1,0]
	v_pk_mul_f32 v[18:19], v[18:19], v[190:191] op_sel_hi:[1,0]
	v_pk_mul_f32 v[16:17], v[16:17], v[190:191] op_sel_hi:[1,0]
	v_pk_mul_f32 v[10:11], v[10:11], v[190:191] op_sel_hi:[1,0]
	v_pk_mul_f32 v[8:9], v[8:9], v[190:191] op_sel_hi:[1,0]
	v_sub_f32_e32 v182, v182, v189
	v_sub_f32_e32 v183, v183, v189
	v_sub_f32_e32 v184, v184, v189
	v_sub_f32_e32 v185, v185, v189
	v_sub_f32_e32 v186, v186, v189
	v_sub_f32_e32 v187, v187, v189

.LBB0_723:
	v_exp_f32_e32 v1, v176
	v_exp_f32_e32 v2, v177
	v_exp_f32_e32 v3, v178
	v_exp_f32_e32 v176, v179
	v_exp_f32_e32 v177, v172
	v_exp_f32_e32 v178, v173
	v_cvt_pk_bf16_f32 v172, v1, v2
	v_cvt_pk_bf16_f32 v173, v3, v176
	v_mov_b32_e32 v1, v0
	v_mov_b32_e32 v2, v0
	v_mov_b32_e32 v3, v0
	v_exp_f32_e32 v175, v175
	v_exp_f32_e32 v179, v174
	v_cvt_pk_bf16_f32 v174, v177, v178
	v_cvt_pk_bf16_f32 v175, v179, v175
	s_nop 0
	v_mfma_f32_16x16x32_bf16 v[164:167], v[0:3], v[172:175], v[164:167]
	v_add_u32_e32 v1, 64, v188
	ds_read_b128 v[176:179], v1 offset:0
	ds_read_b128 v[184:187], v1 offset:2304
	ds_read_b128 v[188:191], v1 offset:4608
	ds_read_b128 v[230:233], v1 offset:6912
	ds_read_b128 v[234:237], v1 offset:9216
	ds_read_b128 v[238:241], v1 offset:11520
	s_waitcnt lgkmcnt(5)
	v_mfma_f32_16x16x32_bf16 v[160:163], v[176:179], v[180:183], v[160:163]
	v_mfma_f32_16x16x32_bf16 v[156:159], v[176:179], v[172:175], v[156:159]
	ds_read_b128 v[176:179], v1 offset:13824
	s_waitcnt lgkmcnt(5)
	v_mfma_f32_16x16x32_bf16 v[152:155], v[184:187], v[180:183], v[152:155]
	v_mfma_f32_16x16x32_bf16 v[148:151], v[184:187], v[172:175], v[148:151]
	ds_read_b128 v[184:187], v1 offset:16128
	s_waitcnt lgkmcnt(5)
	v_mfma_f32_16x16x32_bf16 v[144:147], v[188:191], v[180:183], v[144:147]
	v_mfma_f32_16x16x32_bf16 v[140:143], v[188:191], v[172:175], v[140:143]
	ds_read_b128 v[188:191], v1 offset:18432
	s_waitcnt lgkmcnt(5)
	v_mfma_f32_16x16x32_bf16 v[136:139], v[230:233], v[180:183], v[136:139]
	v_mfma_f32_16x16x32_bf16 v[132:135], v[230:233], v[172:175], v[132:135]
	ds_read_b128 v[230:233], v1 offset:20736
	s_waitcnt lgkmcnt(5)
	v_mfma_f32_16x16x32_bf16 v[96:99], v[234:237], v[180:183], v[96:99]
	v_mfma_f32_16x16x32_bf16 v[92:95], v[234:237], v[172:175], v[92:95]
	ds_read_b128 v[234:237], v1 offset:23040
	s_waitcnt lgkmcnt(5)
	v_mfma_f32_16x16x32_bf16 v[88:91], v[238:241], v[180:183], v[88:91]
	v_mfma_f32_16x16x32_bf16 v[84:87], v[238:241], v[172:175], v[84:87]
	ds_read_b128 v[238:241], v1 offset:25344
	s_waitcnt lgkmcnt(5)
	v_mfma_f32_16x16x32_bf16 v[80:83], v[176:179], v[180:183], v[80:83]
	v_mfma_f32_16x16x32_bf16 v[76:79], v[176:179], v[172:175], v[76:79]
	ds_read_b128 v[176:179], v1 offset:27648
	s_waitcnt lgkmcnt(5)
	v_mfma_f32_16x16x32_bf16 v[72:75], v[184:187], v[180:183], v[72:75]
	v_mfma_f32_16x16x32_bf16 v[68:71], v[184:187], v[172:175], v[68:71]
	ds_read_b128 v[184:187], v1 offset:29952
	s_waitcnt lgkmcnt(5)
	v_mfma_f32_16x16x32_bf16 v[64:67], v[188:191], v[180:183], v[64:67]
	v_mfma_f32_16x16x32_bf16 v[60:63], v[188:191], v[172:175], v[60:63]
	ds_read_b128 v[188:191], v1 offset:32256
	s_waitcnt lgkmcnt(5)
	v_mfma_f32_16x16x32_bf16 v[56:59], v[230:233], v[180:183], v[56:59]
	v_mfma_f32_16x16x32_bf16 v[52:55], v[230:233], v[172:175], v[52:55]
	ds_read_b128 v[230:233], v1 offset:34560
	s_waitcnt lgkmcnt(5)
	v_mfma_f32_16x16x32_bf16 v[48:51], v[234:237], v[180:183], v[48:51]
	v_mfma_f32_16x16x32_bf16 v[44:47], v[234:237], v[172:175], v[44:47]
	s_waitcnt lgkmcnt(4)
	v_mfma_f32_16x16x32_bf16 v[40:43], v[238:241], v[180:183], v[40:43]
	v_mfma_f32_16x16x32_bf16 v[36:39], v[238:241], v[172:175], v[36:39]
	s_waitcnt lgkmcnt(3)
	v_mfma_f32_16x16x32_bf16 v[32:35], v[176:179], v[180:183], v[32:35]
	v_mfma_f32_16x16x32_bf16 v[28:31], v[176:179], v[172:175], v[28:31]
	s_waitcnt lgkmcnt(2)
	v_mfma_f32_16x16x32_bf16 v[24:27], v[184:187], v[180:183], v[24:27]
	v_mfma_f32_16x16x32_bf16 v[20:23], v[184:187], v[172:175], v[20:23]
	s_waitcnt lgkmcnt(1)
	v_mfma_f32_16x16x32_bf16 v[16:19], v[188:191], v[180:183], v[16:19]
	v_mfma_f32_16x16x32_bf16 v[12:15], v[188:191], v[172:175], v[12:15]
	s_waitcnt lgkmcnt(0)
	v_mfma_f32_16x16x32_bf16 v[8:11], v[230:233], v[180:183], v[8:11]
	v_mfma_f32_16x16x32_bf16 v[4:7], v[230:233], v[172:175], v[4:7]
